# FFN-in SSQ LDS cache plus: epilogue's seven permlane32 swap/copy pairs removed (cached half-sums written to both add operands)
# baseline (speedup 1.0000x reference)
.LBB0_557:
	s_add_u32 s60, s58, 0xfffc0080
	s_addc_u32 s61, s59, -1
	s_add_i32 s72, 0, 0x10000
	v_add_u32_e32 v96, s72, v193
	s_cmp_eq_u32 s71, 12
	s_cselect_b32 s63, s49, s61
	s_cselect_b32 s62, s67, s60
	s_cselect_b32 s61, s47, s70
	s_cselect_b32 s60, s68, s69
	s_add_i32 m0, s27, 0xc000
	ds_read_b128 v[160:163], v195
	ds_read_b128 v[164:167], v195 offset:1024
	ds_read_b128 v[168:171], v195 offset:2048
	ds_read_b128 v[172:175], v195 offset:3072
	ds_read_b128 v[182:185], v195 offset:4096
	ds_read_b128 v[186:189], v195 offset:5120
	ds_read_b128 v[196:199], v195 offset:6144
	ds_read_b128 v[200:203], v195 offset:7168
	global_load_lds_dwordx4 v156, s[58:59]
	s_add_i32 m0, s27, 0xe000
	s_nop 0
	global_load_lds_dwordx4 v158, s[58:59]
	s_setprio 1
	s_barrier
	s_waitcnt lgkmcnt(0)
	v_mfma_f32_16x16x32_bf16 v[142:145], v[80:83], v[160:163], v[142:145]
	v_mfma_f32_16x16x32_bf16 v[138:141], v[102:105], v[160:163], v[138:141]
	v_mfma_f32_16x16x32_bf16 v[126:129], v[80:83], v[168:171], v[126:129]
	v_mfma_f32_16x16x32_bf16 v[122:125], v[102:105], v[168:171], v[122:125]
	v_mfma_f32_16x16x32_bf16 v[110:113], v[80:83], v[182:185], v[110:113]
	v_mfma_f32_16x16x32_bf16 v[98:101], v[102:105], v[182:185], v[98:101]
	v_mfma_f32_16x16x32_bf16 v[76:79], v[80:83], v[196:199], v[76:79]
	v_mfma_f32_16x16x32_bf16 v[72:75], v[102:105], v[196:199], v[72:75]
	v_mfma_f32_16x16x32_bf16 v[142:145], v[88:91], v[164:167], v[142:145]
	v_mfma_f32_16x16x32_bf16 v[138:141], v[106:109], v[164:167], v[138:141]
	v_mfma_f32_16x16x32_bf16 v[126:129], v[88:91], v[172:175], v[126:129]
	v_mfma_f32_16x16x32_bf16 v[122:125], v[106:109], v[172:175], v[122:125]
	v_mfma_f32_16x16x32_bf16 v[110:113], v[88:91], v[186:189], v[110:113]
	v_mfma_f32_16x16x32_bf16 v[98:101], v[106:109], v[186:189], v[98:101]
	v_mfma_f32_16x16x32_bf16 v[76:79], v[88:91], v[200:203], v[76:79]
	v_mfma_f32_16x16x32_bf16 v[72:75], v[106:109], v[200:203], v[72:75]
	s_barrier
	s_setprio 0
	s_add_i32 s76, 0, 0x14000
	s_add_i32 s72, s72, s18
	v_add_u32_e32 v96, s76, v193
	v_lshl_add_u64 v[176:177], s[60:61], 0, v[150:151]
	s_mov_b32 m0, s72
	ds_read_b128 v[224:227], v96
	ds_read_b128 v[228:231], v96 offset:1024
	ds_read_b128 v[232:235], v96 offset:2048
	ds_read_b128 v[236:239], v96 offset:3072
	global_load_lds_dwordx4 v150, s[60:61]
	v_lshl_add_u64 v[190:191], s[60:61], 0, v[146:147]
	s_add_i32 m0, s72, 0x2000
	s_nop 0
	global_load_lds_dwordx4 v146, s[60:61]
	s_setprio 1
	s_barrier
	s_waitcnt lgkmcnt(0)
	v_mfma_f32_16x16x32_bf16 v[134:137], v[224:227], v[160:163], v[134:137]
	v_mfma_f32_16x16x32_bf16 v[130:133], v[232:235], v[160:163], v[130:133]
	v_mfma_f32_16x16x32_bf16 v[118:121], v[224:227], v[168:171], v[118:121]
	s_mov_b32 m0, s27
	v_mfma_f32_16x16x32_bf16 v[114:117], v[232:235], v[168:171], v[114:117]
	v_lshl_add_u64 v[240:241], s[62:63], 0, v[152:153]
	v_mfma_f32_16x16x32_bf16 v[92:95], v[224:227], v[182:185], v[92:95]
	v_mfma_f32_16x16x32_bf16 v[84:87], v[232:235], v[182:185], v[84:87]
	v_mfma_f32_16x16x32_bf16 v[68:71], v[224:227], v[196:199], v[68:71]
	v_mfma_f32_16x16x32_bf16 v[64:67], v[232:235], v[196:199], v[64:67]
	v_mfma_f32_16x16x32_bf16 v[134:137], v[228:231], v[164:167], v[134:137]
	v_mfma_f32_16x16x32_bf16 v[130:133], v[236:239], v[164:167], v[130:133]
	v_mfma_f32_16x16x32_bf16 v[118:121], v[228:231], v[172:175], v[118:121]
	v_mfma_f32_16x16x32_bf16 v[114:117], v[236:239], v[172:175], v[114:117]
	v_mfma_f32_16x16x32_bf16 v[92:95], v[228:231], v[186:189], v[92:95]
	v_mfma_f32_16x16x32_bf16 v[84:87], v[236:239], v[186:189], v[84:87]
	v_mfma_f32_16x16x32_bf16 v[68:71], v[228:231], v[200:203], v[68:71]
	v_mfma_f32_16x16x32_bf16 v[64:67], v[236:239], v[200:203], v[64:67]
	s_barrier
	s_setprio 0
	ds_read_b128 v[160:163], v195 offset:16384
	ds_read_b128 v[164:167], v195 offset:17408
	ds_read_b128 v[168:171], v195 offset:18432
	ds_read_b128 v[172:175], v195 offset:19456
	ds_read_b128 v[182:185], v195 offset:20480
	ds_read_b128 v[186:189], v195 offset:21504
	ds_read_b128 v[196:199], v195 offset:22528
	ds_read_b128 v[200:203], v195 offset:23552
	global_load_lds_dwordx4 v152, s[62:63]
	v_lshl_add_u64 v[242:243], s[62:63], 0, v[148:149]
	s_mov_b32 m0, s28
	s_nop 0
	global_load_lds_dwordx4 v148, s[62:63]
	s_waitcnt vmcnt(10)
	s_setprio 1
	s_barrier
	s_waitcnt lgkmcnt(0)
	v_mfma_f32_16x16x32_bf16 v[60:63], v[80:83], v[160:163], v[60:63]
	v_mfma_f32_16x16x32_bf16 v[56:59], v[102:105], v[160:163], v[56:59]
	v_mfma_f32_16x16x32_bf16 v[44:47], v[80:83], v[168:171], v[44:47]
	v_mfma_f32_16x16x32_bf16 v[40:43], v[102:105], v[168:171], v[40:43]
	v_mfma_f32_16x16x32_bf16 v[28:31], v[80:83], v[182:185], v[28:31]
	v_mfma_f32_16x16x32_bf16 v[24:27], v[102:105], v[182:185], v[24:27]
	v_mfma_f32_16x16x32_bf16 v[12:15], v[80:83], v[196:199], v[12:15]
	v_mfma_f32_16x16x32_bf16 v[8:11], v[102:105], v[196:199], v[8:11]
	v_mfma_f32_16x16x32_bf16 v[60:63], v[88:91], v[164:167], v[60:63]
	v_mfma_f32_16x16x32_bf16 v[56:59], v[106:109], v[164:167], v[56:59]
	v_mfma_f32_16x16x32_bf16 v[44:47], v[88:91], v[172:175], v[44:47]
	v_mfma_f32_16x16x32_bf16 v[40:43], v[106:109], v[172:175], v[40:43]
	v_mfma_f32_16x16x32_bf16 v[28:31], v[88:91], v[186:189], v[28:31]
	v_mfma_f32_16x16x32_bf16 v[24:27], v[106:109], v[186:189], v[24:27]
	v_mfma_f32_16x16x32_bf16 v[12:15], v[88:91], v[200:203], v[12:15]
	v_mfma_f32_16x16x32_bf16 v[8:11], v[106:109], v[200:203], v[8:11]
	s_barrier
	s_setprio 0
	v_add_u32_e32 v96, 0x18000, v193
	ds_read_b128 v[80:83], v96
	ds_read_b128 v[88:91], v96 offset:1024
	ds_read_b128 v[102:105], v96 offset:2048
	ds_read_b128 v[106:109], v96 offset:3072
	s_add_u32 s74, s60, 0x40000
	s_addc_u32 s75, s61, 0
	s_add_i32 s72, s76, s18
	s_mov_b32 m0, s72
	s_nop 0
	global_load_lds_dwordx4 v150, s[74:75]
	s_add_i32 m0, s72, 0x2000
	s_nop 0
	global_load_lds_dwordx4 v146, s[74:75]
	s_waitcnt vmcnt(6)
	s_setprio 1
	s_barrier
	v_mfma_f32_16x16x32_bf16 v[52:55], v[224:227], v[160:163], v[52:55]
	v_mfma_f32_16x16x32_bf16 v[48:51], v[232:235], v[160:163], v[48:51]
	v_mfma_f32_16x16x32_bf16 v[36:39], v[224:227], v[168:171], v[36:39]
	s_add_i32 s72, 0, 0x18000
	v_mfma_f32_16x16x32_bf16 v[32:35], v[232:235], v[168:171], v[32:35]
	v_add_u32_e32 v96, s72, v193
	v_mfma_f32_16x16x32_bf16 v[20:23], v[224:227], v[182:185], v[20:23]
	v_mfma_f32_16x16x32_bf16 v[16:19], v[232:235], v[182:185], v[16:19]
	v_mfma_f32_16x16x32_bf16 v[4:7], v[224:227], v[196:199], v[4:7]
	v_mfma_f32_16x16x32_bf16 v[0:3], v[232:235], v[196:199], v[0:3]
	v_mfma_f32_16x16x32_bf16 v[52:55], v[228:231], v[164:167], v[52:55]
	v_mfma_f32_16x16x32_bf16 v[48:51], v[236:239], v[164:167], v[48:51]
	v_mfma_f32_16x16x32_bf16 v[36:39], v[228:231], v[172:175], v[36:39]
	v_mfma_f32_16x16x32_bf16 v[32:35], v[236:239], v[172:175], v[32:35]
	v_mfma_f32_16x16x32_bf16 v[20:23], v[228:231], v[186:189], v[20:23]
	v_mfma_f32_16x16x32_bf16 v[16:19], v[236:239], v[186:189], v[16:19]
	v_mfma_f32_16x16x32_bf16 v[4:7], v[228:231], v[200:203], v[4:7]
	v_mfma_f32_16x16x32_bf16 v[0:3], v[236:239], v[200:203], v[0:3]
	s_barrier
	s_setprio 0
	s_add_u32 s62, s62, 0x40000
	s_addc_u32 s63, s63, 0
	s_mov_b32 m0, s37
	ds_read_b128 v[160:163], v195 offset:32768
	ds_read_b128 v[164:167], v195 offset:33792
	ds_read_b128 v[168:171], v195 offset:34816
	ds_read_b128 v[172:175], v195 offset:35840
	ds_read_b128 v[182:185], v195 offset:36864
	ds_read_b128 v[186:189], v195 offset:37888
	ds_read_b128 v[196:199], v195 offset:38912
	ds_read_b128 v[200:203], v195 offset:39936
	global_load_lds_dwordx4 v152, s[62:63]
	s_mov_b32 m0, s56
	s_nop 0
	global_load_lds_dwordx4 v148, s[62:63]
	s_setprio 1
	s_barrier
	s_waitcnt lgkmcnt(0)
	v_mfma_f32_16x16x32_bf16 v[142:145], v[80:83], v[160:163], v[142:145]
	v_mfma_f32_16x16x32_bf16 v[138:141], v[102:105], v[160:163], v[138:141]
	v_mfma_f32_16x16x32_bf16 v[126:129], v[80:83], v[168:171], v[126:129]
	v_mfma_f32_16x16x32_bf16 v[122:125], v[102:105], v[168:171], v[122:125]
	v_mfma_f32_16x16x32_bf16 v[110:113], v[80:83], v[182:185], v[110:113]
	v_mfma_f32_16x16x32_bf16 v[98:101], v[102:105], v[182:185], v[98:101]
	v_mfma_f32_16x16x32_bf16 v[76:79], v[80:83], v[196:199], v[76:79]
	v_mfma_f32_16x16x32_bf16 v[72:75], v[102:105], v[196:199], v[72:75]
	v_mfma_f32_16x16x32_bf16 v[142:145], v[88:91], v[164:167], v[142:145]
	v_mfma_f32_16x16x32_bf16 v[138:141], v[106:109], v[164:167], v[138:141]
	v_mfma_f32_16x16x32_bf16 v[126:129], v[88:91], v[172:175], v[126:129]
	v_mfma_f32_16x16x32_bf16 v[122:125], v[106:109], v[172:175], v[122:125]
	v_mfma_f32_16x16x32_bf16 v[110:113], v[88:91], v[186:189], v[110:113]
	v_mfma_f32_16x16x32_bf16 v[98:101], v[106:109], v[186:189], v[98:101]
	v_mfma_f32_16x16x32_bf16 v[76:79], v[88:91], v[200:203], v[76:79]
	v_mfma_f32_16x16x32_bf16 v[72:75], v[106:109], v[200:203], v[72:75]
	s_barrier
	s_setprio 0
	s_add_i32 s62, 0, 0x1c000
	s_add_i32 s63, s72, s18
	v_add_u32_e32 v96, s62, v193
	v_lshl_add_u64 v[176:177], v[176:177], 0, s[6:7]
	s_mov_b32 m0, s63
	ds_read_b128 v[224:227], v96
	ds_read_b128 v[228:231], v96 offset:1024
	ds_read_b128 v[232:235], v96 offset:2048
	ds_read_b128 v[236:239], v96 offset:3072
	global_load_lds_dwordx4 v[176:177], off
	v_lshl_add_u64 v[176:177], v[190:191], 0, s[6:7]
	s_add_i32 m0, s63, 0x2000
	s_nop 0
	global_load_lds_dwordx4 v[176:177], off
	s_setprio 1
	s_barrier
	s_waitcnt lgkmcnt(0)
	v_mfma_f32_16x16x32_bf16 v[134:137], v[224:227], v[160:163], v[134:137]
	v_mfma_f32_16x16x32_bf16 v[130:133], v[232:235], v[160:163], v[130:133]
	v_mfma_f32_16x16x32_bf16 v[118:121], v[224:227], v[168:171], v[118:121]
	s_mov_b32 m0, s64
	v_mfma_f32_16x16x32_bf16 v[114:117], v[232:235], v[168:171], v[114:117]
	v_lshl_add_u64 v[176:177], v[240:241], 0, s[6:7]
	v_mfma_f32_16x16x32_bf16 v[92:95], v[224:227], v[182:185], v[92:95]
	v_mfma_f32_16x16x32_bf16 v[84:87], v[232:235], v[182:185], v[84:87]
	v_mfma_f32_16x16x32_bf16 v[68:71], v[224:227], v[196:199], v[68:71]
	v_mfma_f32_16x16x32_bf16 v[64:67], v[232:235], v[196:199], v[64:67]
	v_mfma_f32_16x16x32_bf16 v[134:137], v[228:231], v[164:167], v[134:137]
	v_mfma_f32_16x16x32_bf16 v[130:133], v[236:239], v[164:167], v[130:133]
	v_mfma_f32_16x16x32_bf16 v[118:121], v[228:231], v[172:175], v[118:121]
	v_mfma_f32_16x16x32_bf16 v[114:117], v[236:239], v[172:175], v[114:117]
	v_mfma_f32_16x16x32_bf16 v[92:95], v[228:231], v[186:189], v[92:95]
	v_mfma_f32_16x16x32_bf16 v[84:87], v[236:239], v[186:189], v[84:87]
	v_mfma_f32_16x16x32_bf16 v[68:71], v[228:231], v[200:203], v[68:71]
	v_mfma_f32_16x16x32_bf16 v[64:67], v[236:239], v[200:203], v[64:67]
	s_barrier
	s_setprio 0
	ds_read_b128 v[160:163], v195 offset:49152
	ds_read_b128 v[164:167], v195 offset:50176
	ds_read_b128 v[168:171], v195 offset:51200
	ds_read_b128 v[172:175], v195 offset:52224
	ds_read_b128 v[182:185], v195 offset:53248
	ds_read_b128 v[186:189], v195 offset:54272
	ds_read_b128 v[196:199], v195 offset:55296
	ds_read_b128 v[200:203], v195 offset:56320
	global_load_lds_dwordx4 v[176:177], off
	v_lshl_add_u64 v[176:177], v[242:243], 0, s[6:7]
	s_mov_b32 m0, s65
	s_nop 0
	global_load_lds_dwordx4 v[176:177], off
	s_waitcnt vmcnt(10)
	s_setprio 1
	s_barrier
	s_waitcnt lgkmcnt(0)
	v_mfma_f32_16x16x32_bf16 v[60:63], v[80:83], v[160:163], v[60:63]
	v_mfma_f32_16x16x32_bf16 v[56:59], v[102:105], v[160:163], v[56:59]
	v_mfma_f32_16x16x32_bf16 v[44:47], v[80:83], v[168:171], v[44:47]
	v_mfma_f32_16x16x32_bf16 v[40:43], v[102:105], v[168:171], v[40:43]
	v_mfma_f32_16x16x32_bf16 v[28:31], v[80:83], v[182:185], v[28:31]
	v_mfma_f32_16x16x32_bf16 v[24:27], v[102:105], v[182:185], v[24:27]
	v_mfma_f32_16x16x32_bf16 v[12:15], v[80:83], v[196:199], v[12:15]
	v_mfma_f32_16x16x32_bf16 v[8:11], v[102:105], v[196:199], v[8:11]
	v_mfma_f32_16x16x32_bf16 v[60:63], v[88:91], v[164:167], v[60:63]
	v_mfma_f32_16x16x32_bf16 v[56:59], v[106:109], v[164:167], v[56:59]
	v_mfma_f32_16x16x32_bf16 v[44:47], v[88:91], v[172:175], v[44:47]
	v_mfma_f32_16x16x32_bf16 v[40:43], v[106:109], v[172:175], v[40:43]
	v_mfma_f32_16x16x32_bf16 v[28:31], v[88:91], v[186:189], v[28:31]
	v_mfma_f32_16x16x32_bf16 v[24:27], v[106:109], v[186:189], v[24:27]
	v_mfma_f32_16x16x32_bf16 v[12:15], v[88:91], v[200:203], v[12:15]
	v_mfma_f32_16x16x32_bf16 v[8:11], v[106:109], v[200:203], v[8:11]
	s_barrier
	s_setprio 0
	v_add_u32_e32 v96, 0x10000, v193
	ds_read_b128 v[80:83], v96
	ds_read_b128 v[88:91], v96 offset:1024
	ds_read_b128 v[102:105], v96 offset:2048
	ds_read_b128 v[106:109], v96 offset:3072
	s_add_u32 s60, s60, 0x40080
	s_addc_u32 s61, s61, 0
	s_add_i32 s62, s62, s18
	s_mov_b32 m0, s62
	s_nop 0
	global_load_lds_dwordx4 v150, s[60:61]
	s_add_i32 m0, s62, 0x2000
	s_nop 0
	global_load_lds_dwordx4 v146, s[60:61]
	s_waitcnt vmcnt(6)
	s_setprio 1
	s_barrier
	v_mfma_f32_16x16x32_bf16 v[52:55], v[224:227], v[160:163], v[52:55]
	v_mfma_f32_16x16x32_bf16 v[48:51], v[232:235], v[160:163], v[48:51]
	v_mfma_f32_16x16x32_bf16 v[36:39], v[224:227], v[168:171], v[36:39]
	s_add_i32 s71, s71, 2
	v_mfma_f32_16x16x32_bf16 v[32:35], v[232:235], v[168:171], v[32:35]
	s_add_u32 s58, s58, 0x100
	v_mfma_f32_16x16x32_bf16 v[20:23], v[224:227], v[182:185], v[20:23]
	s_addc_u32 s59, s59, 0
	v_mfma_f32_16x16x32_bf16 v[16:19], v[232:235], v[182:185], v[16:19]
	s_add_u32 s69, s69, 0x100
	v_mfma_f32_16x16x32_bf16 v[4:7], v[224:227], v[196:199], v[4:7]
	s_addc_u32 s70, s70, 0
	v_mfma_f32_16x16x32_bf16 v[0:3], v[232:235], v[196:199], v[0:3]
	s_cmp_gt_u32 s71, 13
	v_mfma_f32_16x16x32_bf16 v[52:55], v[228:231], v[164:167], v[52:55]
	v_mfma_f32_16x16x32_bf16 v[48:51], v[236:239], v[164:167], v[48:51]
	v_mfma_f32_16x16x32_bf16 v[36:39], v[228:231], v[172:175], v[36:39]
	v_mfma_f32_16x16x32_bf16 v[32:35], v[236:239], v[172:175], v[32:35]
	v_mfma_f32_16x16x32_bf16 v[20:23], v[228:231], v[186:189], v[20:23]
	v_mfma_f32_16x16x32_bf16 v[16:19], v[236:239], v[186:189], v[16:19]
	v_mfma_f32_16x16x32_bf16 v[4:7], v[228:231], v[200:203], v[4:7]
	v_mfma_f32_16x16x32_bf16 v[0:3], v[236:239], v[200:203], v[0:3]
	s_barrier
	s_setprio 0
	s_cbranch_scc0 .LBB0_557
	s_waitcnt lgkmcnt(0)
	s_lshl_b32 s47, s54, 8
	s_add_i32 s47, s47, s57
	v_or_b32_e32 v162, s47, v192
	s_lshl_b32 s100, s57, 2
	s_add_i32 s100, s100, 0x20000
	v_lshl_add_u32 v244, v192, 2, s100
	ds_read_b32 v245, v244 offset:64
	ds_read_b32 v246, v244 offset:128
	ds_read_b32 v247, v244 offset:192
	ds_read_b32 v248, v244 offset:512
	ds_read_b32 v249, v244 offset:576
	ds_read_b32 v250, v244 offset:640
	ds_read_b32 v251, v244 offset:704
	ds_read_b32 v244, v244
	v_or_b32_e32 v190, 16, v162
	v_or_b32_e32 v188, 32, v162
	v_or_b32_e32 v186, 48, v162
	v_add_u32_e32 v184, 0x80, v162
	v_add_u32_e32 v172, 0x90, v162
	v_add_u32_e32 v168, 0xa0, v162
	v_add_u32_e32 v164, 0xb0, v162
	s_cmpk_lt_u32 s47, 0x2000
	s_cselect_b32 s47, 1, 2
	v_mov_b32_e32 v218, s47
	v_cmp_lt_i32_e32 vcc, s23, v162
	v_lshl_or_b32 v166, s55, 8, v194
	v_ashrrev_i32_e32 v167, 31, v166
	v_cndmask_b32_e32 v185, 0, v218, vcc
	v_mul_u32_u24_e32 v82, 0x7600, v185
	v_lshlrev_b32_e32 v96, 2, v82
	v_lshl_add_u64 v[80:81], s[44:45], 0, v[96:97]
	v_lshl_add_u64 v[106:107], v[166:167], 2, v[80:81]
	global_load_dwordx4 v[80:83], v[106:107], off offset:16
	global_load_dwordx4 v[88:91], v[106:107], off
	global_load_dwordx4 v[102:105], v[106:107], off offset:528
	s_nop 0
	global_load_dwordx4 v[106:109], v[106:107], off offset:512
	v_lshl_or_b32 v160, s55, 7, v194
	v_cmp_lt_i32_e32 vcc, s23, v190
	s_waitcnt vmcnt(0)
	s_waitcnt lgkmcnt(0)
	v_add_f32_e32 v96, v244, v244
	v_mov_b32_e32 v201, v245
	v_mov_b32_e32 v199, v246
	v_mov_b32_e32 v197, v247
	v_mov_b32_e32 v191, v248
	v_mov_b32_e32 v187, v249
	v_mov_b32_e32 v169, v250
	v_mov_b32_e32 v163, v251
	v_mov_b32_e32 v202, v245
	v_mov_b32_e32 v200, v246
	v_mov_b32_e32 v198, v247
	v_mov_b32_e32 v196, v248
	v_mov_b32_e32 v189, v249
	v_mov_b32_e32 v173, v250
	v_mov_b32_e32 v165, v251
	v_fmamk_f32 v96, v96, 0x3a800000, v207
	v_rsq_f32_e32 v96, v96
	v_mov_b64_e32 v[170:171], s[42:43]
	v_ashrrev_i32_e32 v161, 31, v160
	v_mad_i64_i32 v[170:171], s[54:55], v162, s31, v[170:171]
	v_lshl_add_u64 v[224:225], v[160:161], 1, v[170:171]
	v_pk_mul_f32 v[182:183], v[82:83], s[0:1] op_sel_hi:[1,0]
	v_pk_mul_f32 v[176:177], v[80:81], s[0:1] op_sel_hi:[1,0]
	v_pk_mul_f32 v[174:175], v[90:91], s[0:1] op_sel_hi:[1,0]
	v_pk_mul_f32 v[170:171], v[88:89], s[0:1] op_sel_hi:[1,0]
	v_mul_f32_e32 v226, 0xbfb8aa3b, v96
	v_pk_fma_f32 v[228:229], v[144:145], v[226:227], v[174:175] op_sel_hi:[1,0,1]
	v_pk_fma_f32 v[230:231], v[142:143], v[226:227], v[170:171] op_sel_hi:[1,0,1]
	v_pk_fma_f32 v[232:233], v[140:141], v[226:227], v[182:183] op_sel_hi:[1,0,1]
	v_pk_fma_f32 v[226:227], v[138:139], v[226:227], v[176:177] op_sel_hi:[1,0,1]
	v_exp_f32_e32 v230, v230
	v_exp_f32_e32 v226, v226
	v_exp_f32_e32 v231, v231
	v_exp_f32_e32 v227, v227
	v_exp_f32_e32 v232, v232
	v_exp_f32_e32 v233, v233
	v_exp_f32_e32 v228, v228
	v_exp_f32_e32 v229, v229
	v_pk_add_f32 v[230:231], v[230:231], 1.0 op_sel_hi:[1,0]
	v_pk_add_f32 v[232:233], v[232:233], 1.0 op_sel_hi:[1,0]
	v_pk_add_f32 v[226:227], v[226:227], 1.0 op_sel_hi:[1,0]
	v_pk_add_f32 v[228:229], v[228:229], 1.0 op_sel_hi:[1,0]
	v_rcp_f32_e32 v230, v230
	v_rcp_f32_e32 v226, v226
	v_rcp_f32_e32 v231, v231
	v_rcp_f32_e32 v227, v227
	v_rcp_f32_e32 v232, v232
	v_rcp_f32_e32 v233, v233
	v_rcp_f32_e32 v228, v228
	v_rcp_f32_e32 v229, v229
	v_pk_fma_f32 v[142:143], v[142:143], v[96:97], v[88:89] op_sel_hi:[1,0,1]
	v_pk_fma_f32 v[140:141], v[140:141], v[96:97], v[82:83] op_sel_hi:[1,0,1]
	v_pk_fma_f32 v[138:139], v[138:139], v[96:97], v[80:81] op_sel_hi:[1,0,1]
	v_pk_fma_f32 v[134:135], v[134:135], v[96:97], v[106:107] op_sel_hi:[1,0,1]
	v_pk_fma_f32 v[132:133], v[132:133], v[96:97], v[104:105] op_sel_hi:[1,0,1]
	v_pk_fma_f32 v[130:131], v[130:131], v[96:97], v[102:103] op_sel_hi:[1,0,1]
	v_pk_fma_f32 v[144:145], v[144:145], v[96:97], v[90:91] op_sel_hi:[1,0,1]
	v_pk_fma_f32 v[136:137], v[136:137], v[96:97], v[108:109] op_sel_hi:[1,0,1]
	v_pk_mul_f32 v[134:135], v[142:143], v[134:135]
	v_pk_mul_f32 v[132:133], v[140:141], v[132:133]
	v_pk_mul_f32 v[130:131], v[138:139], v[130:131]
	v_pk_mul_f32 v[136:137], v[144:145], v[136:137]
	v_pk_mul_f32 v[134:135], v[134:135], v[230:231]
	v_pk_mul_f32 v[138:139], v[132:133], v[232:233]
	v_pk_mul_f32 v[132:133], v[130:131], v[226:227]
	v_cvt_pk_bf16_f32 v130, v134, v135
	v_pk_mul_f32 v[136:137], v[136:137], v[228:229]
	v_cvt_pk_bf16_f32 v131, v136, v137
	v_cvt_pk_bf16_f32 v132, v132, v133
	v_cvt_pk_bf16_f32 v133, v138, v139
	global_store_dwordx4 v[224:225], v[130:133], off
	s_nop 0
	v_cndmask_b32_e32 v130, 0, v218, vcc
	v_cmp_ne_u32_e32 vcc, v130, v185
	s_and_saveexec_b64 s[54:55], vcc
	s_cbranch_execz .LBB0_560
	v_mul_u32_u24_e32 v80, 0x7600, v130
	v_lshlrev_b32_e32 v96, 2, v80
	v_lshl_add_u64 v[80:81], s[44:45], 0, v[96:97]
	v_lshl_add_u64 v[106:107], v[166:167], 2, v[80:81]
	global_load_dwordx4 v[88:91], v[106:107], off
	global_load_dwordx4 v[80:83], v[106:107], off offset:16
	global_load_dwordx4 v[102:105], v[106:107], off offset:528
	s_nop 0
	global_load_dwordx4 v[106:109], v[106:107], off offset:512
	v_mov_b32_e32 v185, v130
	s_waitcnt vmcnt(0)
	v_pk_mul_f32 v[170:171], v[88:89], s[0:1] op_sel_hi:[1,0]
	v_pk_mul_f32 v[174:175], v[90:91], s[0:1] op_sel_hi:[1,0]
	v_pk_mul_f32 v[176:177], v[80:81], s[0:1] op_sel_hi:[1,0]
	v_pk_mul_f32 v[182:183], v[82:83], s[0:1] op_sel_hi:[1,0]
